# v19 + P5 EpiUp loads each SSP quad once per lane-group (8 loads per lane instead of 32) and sums the 4 quads across fq with v_permlane16_swap and v_permlane32_swap
# speedup vs baseline: 1.0384x; 1.0384x over previous
; #define PG8_STAGE(bufoff, gbase, voff) do { _Pragma("unroll") for (int _i = 0; _i < 2; ++_i) \
;         __builtin_amdgcn_global_load_lds((const unsigned*)((const char*)(gbase) + (voff)[_i]), (PG8_LAS unsigned*)(lds + (bufoff) + ldsw + _i * 8192), 16, 0, 0); } while (0)
; #define PG8_LDA(dst, b, h) do { _Pragma("unroll") for (int m = 0; m < 4; ++m) _Pragma("unroll") for (int k = 0; k < 2; ++k) dst[m][k] = *(const PG8_LAS bf16x8*)(lds + PG8_SA(b, h) + aoff + m * 2048 + k * 1024); } while (0)
; #define PG8_LDB(dst, b, h) do { _Pragma("unroll") for (int n = 0; n < 2; ++n) _Pragma("unroll") for (int k = 0; k < 2; ++k) dst[n][k] = *(const PG8_LAS bf16x8*)(lds + PG8_SB(b, h) + boff + n * 2048 + k * 1024); } while (0)
; #define PG8_MMA(ai, bj, At, Bt) do { __builtin_amdgcn_s_setprio(1); _Pragma("unroll") for (int m = 0; m < 4; ++m) _Pragma("unroll") for (int n = 0; n < 2; ++n) _Pragma("unroll") for (int k = 0; k < 2; ++k) \
;         acc[ai][bj][m][n] = __builtin_amdgcn_mfma_f32_16x16x32_bf16(Bt[n][k], At[m][k], acc[ai][bj][m][n], 0, 0, 0); __builtin_amdgcn_s_setprio(0); } while (0)
; #define PG8_WAIT_V(n) asm volatile("s_waitcnt vmcnt(" #n ")" ::: "memory")
; #define PG8_WAIT_L(n) asm volatile("s_waitcnt lgkmcnt(" #n ")" ::: "memory")
; #define PG8_BAR __builtin_amdgcn_s_barrier()
; #define PG8_SCHED __builtin_amdgcn_sched_barrier(0)
; template <class Epi, class Sched, bool ALIGN_EPI = false, bool SP2 = false>
; __device__ __forceinline__ void gemm_phase(PG8_LAS unsigned char* lds, const Gemm g, const Sched& S, const Epi& E) {
;     ...
;             PG8_WAIT_V(8); PG8_WAIT_L(0); PG8_BAR; PG8_MMA(1, 0, At, B0); PG8_MMA(1, 1, At, B1); PG8_BAR; PG8_SCHED;
;             PG8_LDB(B0, 1, 0); PG8_LDB(B1, 1, 1); PG8_SCHED; PG8_LDA(At, 1, 0); PG8_STAGE(PG8_SA(0, 1), a2 + hstep, voffA);
;             PG8_WAIT_V(8); PG8_WAIT_L(0); PG8_BAR; PG8_MMA(0, 0, At, B0); PG8_MMA(0, 1, At, B1); PG8_BAR; PG8_SCHED;
.Lrj_P5_1:
	s_waitcnt lgkmcnt(0)
	s_barrier
	s_setprio 1
	s_waitcnt lgkmcnt(0)
	v_mfma_f32_16x16x32_bf16 v[60:63], v[144:147], v[184:187], v[60:63]
	v_mfma_f32_16x16x32_bf16 v[56:59], v[160:163], v[184:187], v[56:59]
	v_mfma_f32_16x16x32_bf16 v[44:47], v[144:147], v[192:195], v[44:47]
	v_mfma_f32_16x16x32_bf16 v[40:43], v[160:163], v[192:195], v[40:43]
	v_mfma_f32_16x16x32_bf16 v[28:31], v[144:147], v[200:203], v[28:31]
	v_mfma_f32_16x16x32_bf16 v[24:27], v[160:163], v[200:203], v[24:27]
	v_mfma_f32_16x16x32_bf16 v[12:15], v[144:147], v[208:211], v[12:15]
	v_mfma_f32_16x16x32_bf16 v[8:11], v[160:163], v[208:211], v[8:11]
	v_mfma_f32_16x16x32_bf16 v[60:63], v[156:159], v[188:191], v[60:63]
	v_mfma_f32_16x16x32_bf16 v[56:59], v[164:167], v[188:191], v[56:59]
	v_mfma_f32_16x16x32_bf16 v[44:47], v[156:159], v[196:199], v[44:47]
	v_mfma_f32_16x16x32_bf16 v[40:43], v[164:167], v[196:199], v[40:43]
	v_mfma_f32_16x16x32_bf16 v[28:31], v[156:159], v[204:207], v[28:31]
	v_mfma_f32_16x16x32_bf16 v[24:27], v[164:167], v[204:207], v[24:27]
	v_mfma_f32_16x16x32_bf16 v[12:15], v[156:159], v[212:215], v[12:15]
	v_mfma_f32_16x16x32_bf16 v[8:11], v[164:167], v[212:215], v[8:11]
	s_setprio 0
	s_setprio 1
	v_mfma_f32_16x16x32_bf16 v[52:55], v[168:171], v[184:187], v[52:55]
	v_mfma_f32_16x16x32_bf16 v[48:51], v[176:179], v[184:187], v[48:51]
	v_mfma_f32_16x16x32_bf16 v[36:39], v[168:171], v[192:195], v[36:39]
	v_mfma_f32_16x16x32_bf16 v[32:35], v[176:179], v[192:195], v[32:35]
	v_mfma_f32_16x16x32_bf16 v[20:23], v[168:171], v[200:203], v[20:23]
	v_mfma_f32_16x16x32_bf16 v[16:19], v[176:179], v[200:203], v[16:19]
	v_mfma_f32_16x16x32_bf16 v[4:7], v[168:171], v[208:211], v[4:7]
	v_mfma_f32_16x16x32_bf16 v[0:3], v[176:179], v[208:211], v[0:3]
	v_mfma_f32_16x16x32_bf16 v[52:55], v[172:175], v[188:191], v[52:55]
	v_mfma_f32_16x16x32_bf16 v[48:51], v[180:183], v[188:191], v[48:51]
	v_mfma_f32_16x16x32_bf16 v[36:39], v[172:175], v[196:199], v[36:39]
	v_mfma_f32_16x16x32_bf16 v[32:35], v[180:183], v[196:199], v[32:35]
	v_mfma_f32_16x16x32_bf16 v[20:23], v[172:175], v[204:207], v[20:23]
	v_mfma_f32_16x16x32_bf16 v[16:19], v[180:183], v[204:207], v[16:19]
	v_mfma_f32_16x16x32_bf16 v[4:7], v[172:175], v[212:215], v[4:7]
	v_mfma_f32_16x16x32_bf16 v[0:3], v[180:183], v[212:215], v[0:3]
	s_setprio 0
	s_barrier
	s_add_i32 s66, 0, 0x18000
	v_add_u32_e32 v155, s66, v149
	s_add_i32 s67, 0, 0x1c000
	ds_read_b128 v[144:147], v155
	ds_read_b128 v[156:159], v155 offset:1024
	ds_read_b128 v[160:163], v155 offset:2048
	ds_read_b128 v[164:167], v155 offset:3072
	v_add_u32_e32 v155, s67, v149
	ds_read_b128 v[168:171], v155
	ds_read_b128 v[172:175], v155 offset:1024
	ds_read_b128 v[176:179], v155 offset:2048
	ds_read_b128 v[180:183], v155 offset:3072
	s_add_u32 s36, s36, 0x40000
	s_addc_u32 s37, s37, 0
	s_mov_b32 m0, s43
	v_lshl_add_u64 v[224:225], s[36:37], 0, v[134:135]
	ds_read_b128 v[184:187], v153 offset:32768
	ds_read_b128 v[188:191], v153 offset:33792
	ds_read_b128 v[192:195], v153 offset:34816
	ds_read_b128 v[196:199], v153 offset:35840
	ds_read_b128 v[200:203], v153 offset:36864
	ds_read_b128 v[204:207], v153 offset:37888
	ds_read_b128 v[208:211], v153 offset:38912
	ds_read_b128 v[212:215], v153 offset:39936
	global_load_lds_dwordx4 v[224:225], off
	v_lshl_add_u64 v[224:225], s[36:37], 0, v[130:131]
	s_mov_b32 m0, s46
	s_nop 0
	global_load_lds_dwordx4 v[224:225], off
	s_waitcnt vmcnt(8)
	s_waitcnt lgkmcnt(0)
	s_barrier
	s_setprio 1
	s_waitcnt lgkmcnt(0)
	v_mfma_f32_16x16x32_bf16 v[124:127], v[144:147], v[184:187], v[124:127]
	v_mfma_f32_16x16x32_bf16 v[120:123], v[160:163], v[184:187], v[120:123]
	v_mfma_f32_16x16x32_bf16 v[108:111], v[144:147], v[192:195], v[108:111]
	v_mfma_f32_16x16x32_bf16 v[104:107], v[160:163], v[192:195], v[104:107]
	v_mfma_f32_16x16x32_bf16 v[92:95], v[144:147], v[200:203], v[92:95]
	v_mfma_f32_16x16x32_bf16 v[88:91], v[160:163], v[200:203], v[88:91]
	v_mfma_f32_16x16x32_bf16 v[76:79], v[144:147], v[208:211], v[76:79]
	v_mfma_f32_16x16x32_bf16 v[72:75], v[160:163], v[208:211], v[72:75]
	v_mfma_f32_16x16x32_bf16 v[124:127], v[156:159], v[188:191], v[124:127]
	v_mfma_f32_16x16x32_bf16 v[120:123], v[164:167], v[188:191], v[120:123]
	v_mfma_f32_16x16x32_bf16 v[108:111], v[156:159], v[196:199], v[108:111]
	v_mfma_f32_16x16x32_bf16 v[104:107], v[164:167], v[196:199], v[104:107]
	v_mfma_f32_16x16x32_bf16 v[92:95], v[156:159], v[204:207], v[92:95]
	v_mfma_f32_16x16x32_bf16 v[88:91], v[164:167], v[204:207], v[88:91]
	v_mfma_f32_16x16x32_bf16 v[76:79], v[156:159], v[212:215], v[76:79]
	v_mfma_f32_16x16x32_bf16 v[72:75], v[164:167], v[212:215], v[72:75]
	s_setprio 0
	s_setprio 1
	v_mfma_f32_16x16x32_bf16 v[116:119], v[168:171], v[184:187], v[116:119]
	v_mfma_f32_16x16x32_bf16 v[112:115], v[176:179], v[184:187], v[112:115]
	v_mfma_f32_16x16x32_bf16 v[100:103], v[168:171], v[192:195], v[100:103]
	v_mfma_f32_16x16x32_bf16 v[96:99], v[176:179], v[192:195], v[96:99]
	v_mfma_f32_16x16x32_bf16 v[84:87], v[168:171], v[200:203], v[84:87]
	v_mfma_f32_16x16x32_bf16 v[80:83], v[176:179], v[200:203], v[80:83]
	v_mfma_f32_16x16x32_bf16 v[68:71], v[168:171], v[208:211], v[68:71]
	v_mfma_f32_16x16x32_bf16 v[64:67], v[176:179], v[208:211], v[64:67]
	v_mfma_f32_16x16x32_bf16 v[116:119], v[172:175], v[188:191], v[116:119]
	v_mfma_f32_16x16x32_bf16 v[112:115], v[180:183], v[188:191], v[112:115]
	v_mfma_f32_16x16x32_bf16 v[100:103], v[172:175], v[196:199], v[100:103]
	v_mfma_f32_16x16x32_bf16 v[96:99], v[180:183], v[196:199], v[96:99]
	v_mfma_f32_16x16x32_bf16 v[84:87], v[172:175], v[204:207], v[84:87]
	v_mfma_f32_16x16x32_bf16 v[80:83], v[180:183], v[204:207], v[80:83]
	v_mfma_f32_16x16x32_bf16 v[68:71], v[172:175], v[212:215], v[68:71]
	v_mfma_f32_16x16x32_bf16 v[64:67], v[180:183], v[212:215], v[64:67]
	s_setprio 0
	s_barrier
; #define PG8_STAGE(bufoff, gbase, voff) do { _Pragma("unroll") for (int _i = 0; _i < 2; ++_i) \
;         __builtin_amdgcn_global_load_lds((const unsigned*)((const char*)(gbase) + (voff)[_i]), (PG8_LAS unsigned*)(lds + (bufoff) + ldsw + _i * 8192), 16, 0, 0); } while (0)
; #define PG8_LDA(dst, b, h) do { _Pragma("unroll") for (int m = 0; m < 4; ++m) _Pragma("unroll") for (int k = 0; k < 2; ++k) dst[m][k] = *(const PG8_LAS bf16x8*)(lds + PG8_SA(b, h) + aoff + m * 2048 + k * 1024); } while (0)
; #define PG8_MMA(ai, bj, At, Bt) do { __builtin_amdgcn_s_setprio(1); _Pragma("unroll") for (int m = 0; m < 4; ++m) _Pragma("unroll") for (int n = 0; n < 2; ++n) _Pragma("unroll") for (int k = 0; k < 2; ++k) \
;         acc[ai][bj][m][n] = __builtin_amdgcn_mfma_f32_16x16x32_bf16(Bt[n][k], At[m][k], acc[ai][bj][m][n], 0, 0, 0); __builtin_amdgcn_s_setprio(0); } while (0)
; #define PG8_WAIT_V(n) asm volatile("s_waitcnt vmcnt(" #n ")" ::: "memory")
; #define PG8_WAIT_L(n) asm volatile("s_waitcnt lgkmcnt(" #n ")" ::: "memory")
; #define PG8_BAR __builtin_amdgcn_s_barrier()
; #define PG8_SCHED __builtin_amdgcn_sched_barrier(0)
; template <class Epi, class Sched, bool ALIGN_EPI = false, bool SP2 = false>
; __device__ __forceinline__ void gemm_phase(PG8_LAS unsigned char* lds, const Gemm g, const Sched& S, const Epi& E) {
;     ...
;             PG8_LDA(At, 1, 1); PG8_STAGE(PG8_SB(1, 0), b3, voffB); PG8_STAGE(PG8_SB(1, 1), b3 + hstep, voffB); PG8_STAGE(PG8_SA(1, 0), a3, voffA);
;             PG8_WAIT_V(8); PG8_WAIT_L(0); PG8_BAR; PG8_MMA(1, 0, At, B0); PG8_MMA(1, 1, At, B1); PG8_BAR; PG8_SCHED;
;     __device__ __forceinline__ void operator()(const f32x4 (&acc)[2][2][4][2], const Unit& u, int wr, int wc, int fr, int fq) const {
;     ...
;             for (int m = 0; m < 4; ++m) { const int row = rbase + ai * 128 + m * 16; const f32x4* sp = (const f32x4*)(SSP + (size_t)row * 16);
;                 const f32x4 s4 = (sp[0] + sp[1]) + (sp[2] + sp[3]); const float rstd = __builtin_amdgcn_rsqf(((s4[0] + s4[1]) + (s4[2] + s4[3])) * (1.0f / 1024.0f) + EPS);
	s_add_i32 s36, s66, s39
	v_lshl_add_u64 v[216:217], v[216:217], 0, s[14:15]
	s_mov_b32 m0, s36
	ds_read_b128 v[184:187], v153 offset:49152
	ds_read_b128 v[188:191], v153 offset:50176
	ds_read_b128 v[192:195], v153 offset:51200
	ds_read_b128 v[196:199], v153 offset:52224
	ds_read_b128 v[200:203], v153 offset:53248
	ds_read_b128 v[204:207], v153 offset:54272
	ds_read_b128 v[208:211], v153 offset:55296
	ds_read_b128 v[212:215], v153 offset:56320
	global_load_lds_dwordx4 v[216:217], off
	s_add_i32 m0, s36, 0x2000
	s_add_u32 s34, s34, 0x40080
	v_lshl_add_u64 v[216:217], v[218:219], 0, s[14:15]
	s_addc_u32 s35, s35, 0
	s_add_i32 s36, s67, s39
	global_load_lds_dwordx4 v[216:217], off
	v_lshl_add_u64 v[216:217], s[34:35], 0, v[132:133]
	s_mov_b32 m0, s36
	s_nop 0
	global_load_lds_dwordx4 v[216:217], off
	v_lshl_add_u64 v[216:217], s[34:35], 0, v[128:129]
	s_add_i32 m0, s36, 0x2000
	s_nop 0
	global_load_lds_dwordx4 v[216:217], off
	v_lshl_add_u64 v[216:217], v[220:221], 0, s[14:15]
	s_mov_b32 m0, s49
	s_nop 0
	global_load_lds_dwordx4 v[216:217], off
	v_lshl_add_u64 v[216:217], v[222:223], 0, s[14:15]
	s_mov_b32 m0, s50
	s_nop 0
	global_load_lds_dwordx4 v[216:217], off
	s_waitcnt vmcnt(8)
	s_waitcnt lgkmcnt(0)
	s_barrier
	s_setprio 1
	s_waitcnt lgkmcnt(0)
	v_mfma_f32_16x16x32_bf16 v[60:63], v[144:147], v[184:187], v[60:63]
	v_mfma_f32_16x16x32_bf16 v[56:59], v[160:163], v[184:187], v[56:59]
	v_mfma_f32_16x16x32_bf16 v[44:47], v[144:147], v[192:195], v[44:47]
	v_mfma_f32_16x16x32_bf16 v[40:43], v[160:163], v[192:195], v[40:43]
	v_mfma_f32_16x16x32_bf16 v[28:31], v[144:147], v[200:203], v[28:31]
	v_mfma_f32_16x16x32_bf16 v[24:27], v[160:163], v[200:203], v[24:27]
	v_mfma_f32_16x16x32_bf16 v[12:15], v[144:147], v[208:211], v[12:15]
	v_mfma_f32_16x16x32_bf16 v[8:11], v[160:163], v[208:211], v[8:11]
	v_mfma_f32_16x16x32_bf16 v[60:63], v[156:159], v[188:191], v[60:63]
	v_mfma_f32_16x16x32_bf16 v[56:59], v[164:167], v[188:191], v[56:59]
	v_mfma_f32_16x16x32_bf16 v[44:47], v[156:159], v[196:199], v[44:47]
	v_mfma_f32_16x16x32_bf16 v[40:43], v[164:167], v[196:199], v[40:43]
	v_mfma_f32_16x16x32_bf16 v[28:31], v[156:159], v[204:207], v[28:31]
	v_mfma_f32_16x16x32_bf16 v[24:27], v[164:167], v[204:207], v[24:27]
	v_mfma_f32_16x16x32_bf16 v[12:15], v[156:159], v[212:215], v[12:15]
	v_mfma_f32_16x16x32_bf16 v[8:11], v[164:167], v[212:215], v[8:11]
	s_setprio 0
	s_setprio 1
	v_mfma_f32_16x16x32_bf16 v[52:55], v[168:171], v[184:187], v[52:55]
	v_mfma_f32_16x16x32_bf16 v[48:51], v[176:179], v[184:187], v[48:51]
	v_mfma_f32_16x16x32_bf16 v[36:39], v[168:171], v[192:195], v[36:39]
	v_mfma_f32_16x16x32_bf16 v[32:35], v[176:179], v[192:195], v[32:35]
	v_mfma_f32_16x16x32_bf16 v[20:23], v[168:171], v[200:203], v[20:23]
	v_mfma_f32_16x16x32_bf16 v[16:19], v[176:179], v[200:203], v[16:19]
	v_mfma_f32_16x16x32_bf16 v[4:7], v[168:171], v[208:211], v[4:7]
	v_mfma_f32_16x16x32_bf16 v[0:3], v[176:179], v[208:211], v[0:3]
	v_mfma_f32_16x16x32_bf16 v[52:55], v[172:175], v[188:191], v[52:55]
	v_mfma_f32_16x16x32_bf16 v[48:51], v[180:183], v[188:191], v[48:51]
	v_mfma_f32_16x16x32_bf16 v[36:39], v[172:175], v[196:199], v[36:39]
	v_mfma_f32_16x16x32_bf16 v[32:35], v[180:183], v[196:199], v[32:35]
	v_mfma_f32_16x16x32_bf16 v[20:23], v[172:175], v[204:207], v[20:23]
	v_mfma_f32_16x16x32_bf16 v[16:19], v[180:183], v[204:207], v[16:19]
	v_mfma_f32_16x16x32_bf16 v[4:7], v[172:175], v[212:215], v[4:7]
	v_mfma_f32_16x16x32_bf16 v[0:3], v[180:183], v[212:215], v[0:3]
	s_setprio 0
	s_barrier
	s_mov_b32 s99, 0
	s_add_i32 s65, s65, 2
	s_add_u32 s30, s30, 0x100
	s_addc_u32 s31, s31, 0
	s_add_u32 s63, s63, 0x100
	s_addc_u32 s64, s64, 0
	s_cmp_gt_u32 s65, 13
	s_cbranch_scc0 .LBB0_1540
	v_lshl_add_u32 v146, s28, 8, v148
	v_ashrrev_i32_e32 v147, 31, v146
	v_lshlrev_b64 v[144:145], 6, v[146:147]
	v_lshl_add_u64 v[144:145], s[12:13], 0, v[144:145]
	v_bfe_u32 v156, v226, 4, 2
	v_lshlrev_b32_e32 v156, 4, v156
	v_mov_b32_e32 v157, 0
	v_lshl_add_u64 v[144:145], v[144:145], 0, v[156:157]
	s_mov_b64 s[98:99], 0x2000
	v_lshl_add_u64 v[222:223], v[144:145], 0, s[98:99]
	global_load_dwordx4 v[156:159], v[144:145], off
	global_load_dwordx4 v[160:163], v[144:145], off offset:1024
	global_load_dwordx4 v[164:167], v[144:145], off offset:2048
	global_load_dwordx4 v[168:171], v[144:145], off offset:3072
	global_load_dwordx4 v[172:175], v[222:223], off
	global_load_dwordx4 v[176:179], v[222:223], off offset:1024
	global_load_dwordx4 v[180:183], v[222:223], off offset:2048
	global_load_dwordx4 v[184:187], v[222:223], off offset:3072
	s_and_b64 vcc, exec, s[16:17]
	s_cbranch_vccz .LBB0_1543
	s_barrier
; __device__ __forceinline__ u32x4 pack8(const f32x4 a, const f32x4 b) { u32x4 w; w.x = cvt_pk_bf16(a[0], a[1]); w.y = cvt_pk_bf16(a[2], a[3]); w.z = cvt_pk_bf16(b[0], b[1]); w.w = cvt_pk_bf16(b[2], b[3]); return w; }
;     __device__ __forceinline__ void operator()(const f32x4 (&acc)[2][2][4][2], const Unit& u, int wr, int wc, int fr, int fq) const {
;     ...
;             for (int m = 0; m < 4; ++m) { const int row = rbase + ai * 128 + m * 16; const f32x4* sp = (const f32x4*)(SSP + (size_t)row * 16);
;                 const f32x4 s4 = (sp[0] + sp[1]) + (sp[2] + sp[3]); const float rstd = __builtin_amdgcn_rsqf(((s4[0] + s4[1]) + (s4[2] + s4[3])) * (1.0f / 1024.0f) + EPS);
; #pragma unroll
;                 for (int bj = 0; bj < 2; ++bj) { f32x4 v0 = acc[ai][bj][m][0] * rstd, v1 = acc[ai][bj][m][1] * rstd;
; #pragma unroll
;                     for (int i = 0; i < 4; ++i) { const float a = fmaxf(v0[i], 0.f), b = fmaxf(v1[i], 0.f); v0[i] = a * a; v1[i] = b * b; }
;                     *(u32x4*)(Z + (size_t)row * FF + cb + bj * 128) = pack8(v0, v1); }
.LBB0_1543:
	v_lshlrev_b64 v[220:221], 13, v[146:147]
	v_lshl_or_b32 v222, s60, 8, v150
	v_ashrrev_i32_e32 v223, 31, v222
	v_lshlrev_b64 v[222:223], 1, v[222:223]
	v_lshl_add_u64 v[220:221], s[8:9], 0, v[220:221]
	v_lshl_add_u64 v[220:221], v[220:221], 0, v[222:223]
	s_mov_b64 s[100:101], 0xa0000
	s_mov_b64 s[98:99], 0x20000
	s_waitcnt vmcnt(4)
	v_pk_add_f32 v[156:157], v[156:157], v[158:159]
	v_pk_add_f32 v[160:161], v[160:161], v[162:163]
	v_pk_add_f32 v[164:165], v[164:165], v[166:167]
	v_pk_add_f32 v[168:169], v[168:169], v[170:171]
	v_add_f32_e32 v156, v156, v157
	v_add_f32_e32 v160, v160, v161
	v_add_f32_e32 v164, v164, v165
	v_add_f32_e32 v168, v168, v169
	v_mov_b32_e32 v157, v156
	v_mov_b32_e32 v161, v160
	v_mov_b32_e32 v165, v164
	v_mov_b32_e32 v169, v168
	s_nop 1
	v_permlane16_swap_b32_e32 v157, v156
	v_permlane16_swap_b32_e32 v161, v160
	v_permlane16_swap_b32_e32 v165, v164
	v_permlane16_swap_b32_e32 v169, v168
	s_nop 1
	v_add_f32_e32 v156, v156, v157
	v_add_f32_e32 v160, v160, v161
	v_add_f32_e32 v164, v164, v165
	v_add_f32_e32 v168, v168, v169
	v_mov_b32_e32 v157, v156
	v_mov_b32_e32 v161, v160
	v_mov_b32_e32 v165, v164
	v_mov_b32_e32 v169, v168
	s_nop 1
	v_permlane32_swap_b32_e32 v157, v156
	v_permlane32_swap_b32_e32 v161, v160
	v_permlane32_swap_b32_e32 v165, v164
	v_permlane32_swap_b32_e32 v169, v168
	s_nop 1
	v_add_f32_e32 v156, v156, v157
	v_add_f32_e32 v160, v160, v161
	v_add_f32_e32 v164, v164, v165
	v_add_f32_e32 v168, v168, v169
	v_fmamk_f32 v156, v156, 0x3a800000, v154
	v_fmamk_f32 v160, v160, 0x3a800000, v154
	v_fmamk_f32 v164, v164, 0x3a800000, v154
	v_fmamk_f32 v168, v168, 0x3a800000, v154
	v_rsq_f32_e32 v156, v156
	v_rsq_f32_e32 v160, v160
	v_rsq_f32_e32 v164, v164
	v_rsq_f32_e32 v168, v168
	s_nop 0
	v_mul_f32_e32 v112, v156, v112
	v_mul_f32_e32 v113, v156, v113
	v_mul_f32_e32 v114, v156, v114
	v_mul_f32_e32 v115, v156, v115
	v_mul_f32_e32 v116, v156, v116
	v_mul_f32_e32 v117, v156, v117
	v_mul_f32_e32 v118, v156, v118
	v_mul_f32_e32 v119, v156, v119
	v_mul_f32_e32 v120, v156, v120
	v_mul_f32_e32 v121, v156, v121
	v_mul_f32_e32 v122, v156, v122
	v_mul_f32_e32 v123, v156, v123
	v_mul_f32_e32 v124, v156, v124
	v_mul_f32_e32 v125, v156, v125
	v_mul_f32_e32 v126, v156, v126
	v_mul_f32_e32 v127, v156, v127
	v_max_f32_e32 v112, 0, v112
	v_max_f32_e32 v113, 0, v113
	v_max_f32_e32 v114, 0, v114
	v_max_f32_e32 v115, 0, v115
	v_max_f32_e32 v116, 0, v116
	v_max_f32_e32 v117, 0, v117
	v_max_f32_e32 v118, 0, v118
	v_max_f32_e32 v119, 0, v119
	v_max_f32_e32 v120, 0, v120
	v_max_f32_e32 v121, 0, v121
	v_max_f32_e32 v122, 0, v122
	v_max_f32_e32 v123, 0, v123
	v_max_f32_e32 v124, 0, v124
	v_max_f32_e32 v125, 0, v125
	v_max_f32_e32 v126, 0, v126
	v_max_f32_e32 v127, 0, v127
	v_mul_f32_e32 v112, v112, v112
	v_mul_f32_e32 v113, v113, v113
	v_mul_f32_e32 v114, v114, v114
	v_mul_f32_e32 v115, v115, v115
	v_mul_f32_e32 v116, v116, v116
	v_mul_f32_e32 v117, v117, v117
	v_mul_f32_e32 v118, v118, v118
	v_mul_f32_e32 v119, v119, v119
	v_mul_f32_e32 v120, v120, v120
	v_mul_f32_e32 v121, v121, v121
	v_mul_f32_e32 v122, v122, v122
	v_mul_f32_e32 v123, v123, v123
	v_mul_f32_e32 v124, v124, v124
	v_mul_f32_e32 v125, v125, v125
	v_mul_f32_e32 v126, v126, v126
	v_mul_f32_e32 v127, v127, v127
	v_cvt_pk_bf16_f32 v124, v124, v125
	v_cvt_pk_bf16_f32 v125, v126, v127
	v_cvt_pk_bf16_f32 v126, v120, v121
	v_cvt_pk_bf16_f32 v127, v122, v123
	v_cvt_pk_bf16_f32 v116, v116, v117
	v_cvt_pk_bf16_f32 v117, v118, v119
	v_cvt_pk_bf16_f32 v118, v112, v113
	v_cvt_pk_bf16_f32 v119, v114, v115
	global_store_dwordx4 v[220:221], v[124:127], off
	global_store_dwordx4 v[220:221], v[116:119], off offset:256
	v_lshl_add_u64 v[220:221], v[220:221], 0, s[98:99]
	v_mul_f32_e32 v96, v160, v96
	v_mul_f32_e32 v97, v160, v97
	v_mul_f32_e32 v98, v160, v98
	v_mul_f32_e32 v99, v160, v99
	v_mul_f32_e32 v100, v160, v100
	v_mul_f32_e32 v101, v160, v101
	v_mul_f32_e32 v102, v160, v102
	v_mul_f32_e32 v103, v160, v103
	v_mul_f32_e32 v104, v160, v104
	v_mul_f32_e32 v105, v160, v105
	v_mul_f32_e32 v106, v160, v106
	v_mul_f32_e32 v107, v160, v107
	v_mul_f32_e32 v108, v160, v108
	v_mul_f32_e32 v109, v160, v109
	v_mul_f32_e32 v110, v160, v110
	v_mul_f32_e32 v111, v160, v111
	v_max_f32_e32 v96, 0, v96
	v_max_f32_e32 v97, 0, v97
	v_max_f32_e32 v98, 0, v98
	v_max_f32_e32 v99, 0, v99
	v_max_f32_e32 v100, 0, v100
	v_max_f32_e32 v101, 0, v101
	v_max_f32_e32 v102, 0, v102
	v_max_f32_e32 v103, 0, v103
	v_max_f32_e32 v104, 0, v104
	v_max_f32_e32 v105, 0, v105
	v_max_f32_e32 v106, 0, v106
	v_max_f32_e32 v107, 0, v107
	v_max_f32_e32 v108, 0, v108
	v_max_f32_e32 v109, 0, v109
	v_max_f32_e32 v110, 0, v110
	v_max_f32_e32 v111, 0, v111
	v_mul_f32_e32 v96, v96, v96
	v_mul_f32_e32 v97, v97, v97
	v_mul_f32_e32 v98, v98, v98
	v_mul_f32_e32 v99, v99, v99
	v_mul_f32_e32 v100, v100, v100
	v_mul_f32_e32 v101, v101, v101
	v_mul_f32_e32 v102, v102, v102
	v_mul_f32_e32 v103, v103, v103
	v_mul_f32_e32 v104, v104, v104
	v_mul_f32_e32 v105, v105, v105
	v_mul_f32_e32 v106, v106, v106
	v_mul_f32_e32 v107, v107, v107
	v_mul_f32_e32 v108, v108, v108
	v_mul_f32_e32 v109, v109, v109
	v_mul_f32_e32 v110, v110, v110
	v_mul_f32_e32 v111, v111, v111
	v_cvt_pk_bf16_f32 v108, v108, v109
	v_cvt_pk_bf16_f32 v109, v110, v111
	v_cvt_pk_bf16_f32 v110, v104, v105
	v_cvt_pk_bf16_f32 v111, v106, v107
	v_cvt_pk_bf16_f32 v100, v100, v101
	v_cvt_pk_bf16_f32 v101, v102, v103
	v_cvt_pk_bf16_f32 v102, v96, v97
	v_cvt_pk_bf16_f32 v103, v98, v99
	global_store_dwordx4 v[220:221], v[108:111], off
	global_store_dwordx4 v[220:221], v[100:103], off offset:256
	v_lshl_add_u64 v[220:221], v[220:221], 0, s[98:99]
	v_mul_f32_e32 v80, v164, v80
; __device__ __forceinline__ u32x4 pack8(const f32x4 a, const f32x4 b) { u32x4 w; w.x = cvt_pk_bf16(a[0], a[1]); w.y = cvt_pk_bf16(a[2], a[3]); w.z = cvt_pk_bf16(b[0], b[1]); w.w = cvt_pk_bf16(b[2], b[3]); return w; }
;     __device__ __forceinline__ void operator()(const f32x4 (&acc)[2][2][4][2], const Unit& u, int wr, int wc, int fr, int fq) const {
;     ...
;             for (int m = 0; m < 4; ++m) { const int row = rbase + ai * 128 + m * 16; const f32x4* sp = (const f32x4*)(SSP + (size_t)row * 16);
;                 const f32x4 s4 = (sp[0] + sp[1]) + (sp[2] + sp[3]); const float rstd = __builtin_amdgcn_rsqf(((s4[0] + s4[1]) + (s4[2] + s4[3])) * (1.0f / 1024.0f) + EPS);
; #pragma unroll
;                 for (int bj = 0; bj < 2; ++bj) { f32x4 v0 = acc[ai][bj][m][0] * rstd, v1 = acc[ai][bj][m][1] * rstd;
; #pragma unroll
;                     for (int i = 0; i < 4; ++i) { const float a = fmaxf(v0[i], 0.f), b = fmaxf(v1[i], 0.f); v0[i] = a * a; v1[i] = b * b; }
;                     *(u32x4*)(Z + (size_t)row * FF + cb + bj * 128) = pack8(v0, v1); }
	v_mul_f32_e32 v81, v164, v81
	v_mul_f32_e32 v82, v164, v82
	v_mul_f32_e32 v83, v164, v83
	v_mul_f32_e32 v84, v164, v84
	v_mul_f32_e32 v85, v164, v85
	v_mul_f32_e32 v86, v164, v86
	v_mul_f32_e32 v87, v164, v87
	v_mul_f32_e32 v88, v164, v88
	v_mul_f32_e32 v89, v164, v89
	v_mul_f32_e32 v90, v164, v90
	v_mul_f32_e32 v91, v164, v91
	v_mul_f32_e32 v92, v164, v92
	v_mul_f32_e32 v93, v164, v93
	v_mul_f32_e32 v94, v164, v94
	v_mul_f32_e32 v95, v164, v95
	v_max_f32_e32 v80, 0, v80
	v_max_f32_e32 v81, 0, v81
	v_max_f32_e32 v82, 0, v82
	v_max_f32_e32 v83, 0, v83
	v_max_f32_e32 v84, 0, v84
	v_max_f32_e32 v85, 0, v85
	v_max_f32_e32 v86, 0, v86
	v_max_f32_e32 v87, 0, v87
	v_max_f32_e32 v88, 0, v88
	v_max_f32_e32 v89, 0, v89
	v_max_f32_e32 v90, 0, v90
	v_max_f32_e32 v91, 0, v91
	v_max_f32_e32 v92, 0, v92
	v_max_f32_e32 v93, 0, v93
	v_max_f32_e32 v94, 0, v94
	v_max_f32_e32 v95, 0, v95
	v_mul_f32_e32 v80, v80, v80
	v_mul_f32_e32 v81, v81, v81
	v_mul_f32_e32 v82, v82, v82
	v_mul_f32_e32 v83, v83, v83
	v_mul_f32_e32 v84, v84, v84
	v_mul_f32_e32 v85, v85, v85
	v_mul_f32_e32 v86, v86, v86
	v_mul_f32_e32 v87, v87, v87
	v_mul_f32_e32 v88, v88, v88
	v_mul_f32_e32 v89, v89, v89
	v_mul_f32_e32 v90, v90, v90
	v_mul_f32_e32 v91, v91, v91
	v_mul_f32_e32 v92, v92, v92
	v_mul_f32_e32 v93, v93, v93
	v_mul_f32_e32 v94, v94, v94
	v_mul_f32_e32 v95, v95, v95
	v_cvt_pk_bf16_f32 v92, v92, v93
	v_cvt_pk_bf16_f32 v93, v94, v95
	v_cvt_pk_bf16_f32 v94, v88, v89
	v_cvt_pk_bf16_f32 v95, v90, v91
	v_cvt_pk_bf16_f32 v84, v84, v85
	v_cvt_pk_bf16_f32 v85, v86, v87
	v_cvt_pk_bf16_f32 v86, v80, v81
	v_cvt_pk_bf16_f32 v87, v82, v83
	global_store_dwordx4 v[220:221], v[92:95], off
	global_store_dwordx4 v[220:221], v[84:87], off offset:256
	v_lshl_add_u64 v[220:221], v[220:221], 0, s[98:99]
	v_mul_f32_e32 v64, v168, v64
	v_mul_f32_e32 v65, v168, v65
	v_mul_f32_e32 v66, v168, v66
	v_mul_f32_e32 v67, v168, v67
	v_mul_f32_e32 v68, v168, v68
	v_mul_f32_e32 v69, v168, v69
	v_mul_f32_e32 v70, v168, v70
	v_mul_f32_e32 v71, v168, v71
	v_mul_f32_e32 v72, v168, v72
	v_mul_f32_e32 v73, v168, v73
	v_mul_f32_e32 v74, v168, v74
	v_mul_f32_e32 v75, v168, v75
	v_mul_f32_e32 v76, v168, v76
	v_mul_f32_e32 v77, v168, v77
	v_mul_f32_e32 v78, v168, v78
	v_mul_f32_e32 v79, v168, v79
	v_max_f32_e32 v64, 0, v64
	v_max_f32_e32 v65, 0, v65
	v_max_f32_e32 v66, 0, v66
	v_max_f32_e32 v67, 0, v67
	v_max_f32_e32 v68, 0, v68
	v_max_f32_e32 v69, 0, v69
	v_max_f32_e32 v70, 0, v70
	v_max_f32_e32 v71, 0, v71
	v_max_f32_e32 v72, 0, v72
	v_max_f32_e32 v73, 0, v73
	v_max_f32_e32 v74, 0, v74
	v_max_f32_e32 v75, 0, v75
	v_max_f32_e32 v76, 0, v76
	v_max_f32_e32 v77, 0, v77
	v_max_f32_e32 v78, 0, v78
	v_max_f32_e32 v79, 0, v79
	v_mul_f32_e32 v64, v64, v64
	v_mul_f32_e32 v65, v65, v65
	v_mul_f32_e32 v66, v66, v66
	v_mul_f32_e32 v67, v67, v67
	v_mul_f32_e32 v68, v68, v68
	v_mul_f32_e32 v69, v69, v69
	v_mul_f32_e32 v70, v70, v70
	v_mul_f32_e32 v71, v71, v71
	v_mul_f32_e32 v72, v72, v72
	v_mul_f32_e32 v73, v73, v73
	v_mul_f32_e32 v74, v74, v74
	v_mul_f32_e32 v75, v75, v75
	v_mul_f32_e32 v76, v76, v76
	v_mul_f32_e32 v77, v77, v77
	v_mul_f32_e32 v78, v78, v78
	v_mul_f32_e32 v79, v79, v79
	v_cvt_pk_bf16_f32 v76, v76, v77
	v_cvt_pk_bf16_f32 v77, v78, v79
	v_cvt_pk_bf16_f32 v78, v72, v73
	v_cvt_pk_bf16_f32 v79, v74, v75
	v_cvt_pk_bf16_f32 v68, v68, v69
	v_cvt_pk_bf16_f32 v69, v70, v71
	v_cvt_pk_bf16_f32 v70, v64, v65
	v_cvt_pk_bf16_f32 v71, v66, v67
	global_store_dwordx4 v[220:221], v[76:79], off
	global_store_dwordx4 v[220:221], v[68:71], off offset:256
	v_lshl_add_u64 v[220:221], v[220:221], 0, s[100:101]
	s_waitcnt vmcnt(8)
	v_pk_add_f32 v[172:173], v[172:173], v[174:175]
	v_pk_add_f32 v[176:177], v[176:177], v[178:179]
	v_pk_add_f32 v[180:181], v[180:181], v[182:183]
	v_pk_add_f32 v[184:185], v[184:185], v[186:187]
	v_add_f32_e32 v172, v172, v173
	v_add_f32_e32 v176, v176, v177
	v_add_f32_e32 v180, v180, v181
	v_add_f32_e32 v184, v184, v185
	v_mov_b32_e32 v173, v172
	v_mov_b32_e32 v177, v176
	v_mov_b32_e32 v181, v180
	v_mov_b32_e32 v185, v184
	s_nop 1
	v_permlane16_swap_b32_e32 v173, v172
	v_permlane16_swap_b32_e32 v177, v176
	v_permlane16_swap_b32_e32 v181, v180
	v_permlane16_swap_b32_e32 v185, v184
	s_nop 1
	v_add_f32_e32 v172, v172, v173
	v_add_f32_e32 v176, v176, v177
	v_add_f32_e32 v180, v180, v181
	v_add_f32_e32 v184, v184, v185
	v_mov_b32_e32 v173, v172
	v_mov_b32_e32 v177, v176
	v_mov_b32_e32 v181, v180
	v_mov_b32_e32 v185, v184
	s_nop 1
	v_permlane32_swap_b32_e32 v173, v172
	v_permlane32_swap_b32_e32 v177, v176
	v_permlane32_swap_b32_e32 v181, v180
	v_permlane32_swap_b32_e32 v185, v184
	s_nop 1
	v_add_f32_e32 v172, v172, v173
	v_add_f32_e32 v176, v176, v177
	v_add_f32_e32 v180, v180, v181
	v_add_f32_e32 v184, v184, v185
	v_fmamk_f32 v172, v172, 0x3a800000, v154
	v_fmamk_f32 v176, v176, 0x3a800000, v154
	v_fmamk_f32 v180, v180, 0x3a800000, v154
	v_fmamk_f32 v184, v184, 0x3a800000, v154
	v_rsq_f32_e32 v172, v172
	v_rsq_f32_e32 v176, v176
	v_rsq_f32_e32 v180, v180
	v_rsq_f32_e32 v184, v184
	s_nop 0
	v_mul_f32_e32 v48, v172, v48
	v_mul_f32_e32 v49, v172, v49
	v_mul_f32_e32 v50, v172, v50
	v_mul_f32_e32 v51, v172, v51
	v_mul_f32_e32 v52, v172, v52
	v_mul_f32_e32 v53, v172, v53
	v_mul_f32_e32 v54, v172, v54
	v_mul_f32_e32 v55, v172, v55
	v_mul_f32_e32 v56, v172, v56
	v_mul_f32_e32 v57, v172, v57
	v_mul_f32_e32 v58, v172, v58
	v_mul_f32_e32 v59, v172, v59
	v_mul_f32_e32 v60, v172, v60
	v_mul_f32_e32 v61, v172, v61
	v_mul_f32_e32 v62, v172, v62
	v_mul_f32_e32 v63, v172, v63
	v_max_f32_e32 v48, 0, v48
	v_max_f32_e32 v49, 0, v49
	v_max_f32_e32 v50, 0, v50
	v_max_f32_e32 v51, 0, v51
	v_max_f32_e32 v52, 0, v52
	v_max_f32_e32 v53, 0, v53
; __device__ __forceinline__ u32x4 pack8(const f32x4 a, const f32x4 b) { u32x4 w; w.x = cvt_pk_bf16(a[0], a[1]); w.y = cvt_pk_bf16(a[2], a[3]); w.z = cvt_pk_bf16(b[0], b[1]); w.w = cvt_pk_bf16(b[2], b[3]); return w; }
;     __device__ __forceinline__ void operator()(const f32x4 (&acc)[2][2][4][2], const Unit& u, int wr, int wc, int fr, int fq) const {
;     ...
;                 for (int bj = 0; bj < 2; ++bj) { f32x4 v0 = acc[ai][bj][m][0] * rstd, v1 = acc[ai][bj][m][1] * rstd;
; #pragma unroll
;                     for (int i = 0; i < 4; ++i) { const float a = fmaxf(v0[i], 0.f), b = fmaxf(v1[i], 0.f); v0[i] = a * a; v1[i] = b * b; }
;                     *(u32x4*)(Z + (size_t)row * FF + cb + bj * 128) = pack8(v0, v1); }
	v_max_f32_e32 v54, 0, v54
	v_max_f32_e32 v55, 0, v55
	v_max_f32_e32 v56, 0, v56
	v_max_f32_e32 v57, 0, v57
	v_max_f32_e32 v58, 0, v58
	v_max_f32_e32 v59, 0, v59
	v_max_f32_e32 v60, 0, v60
	v_max_f32_e32 v61, 0, v61
	v_max_f32_e32 v62, 0, v62
	v_max_f32_e32 v63, 0, v63
	v_mul_f32_e32 v48, v48, v48
	v_mul_f32_e32 v49, v49, v49
	v_mul_f32_e32 v50, v50, v50
	v_mul_f32_e32 v51, v51, v51
	v_mul_f32_e32 v52, v52, v52
	v_mul_f32_e32 v53, v53, v53
	v_mul_f32_e32 v54, v54, v54
	v_mul_f32_e32 v55, v55, v55
	v_mul_f32_e32 v56, v56, v56
	v_mul_f32_e32 v57, v57, v57
	v_mul_f32_e32 v58, v58, v58
	v_mul_f32_e32 v59, v59, v59
	v_mul_f32_e32 v60, v60, v60
	v_mul_f32_e32 v61, v61, v61
	v_mul_f32_e32 v62, v62, v62
	v_mul_f32_e32 v63, v63, v63
	v_cvt_pk_bf16_f32 v60, v60, v61
	v_cvt_pk_bf16_f32 v61, v62, v63
	v_cvt_pk_bf16_f32 v62, v56, v57
	v_cvt_pk_bf16_f32 v63, v58, v59
	v_cvt_pk_bf16_f32 v52, v52, v53
	v_cvt_pk_bf16_f32 v53, v54, v55
	v_cvt_pk_bf16_f32 v54, v48, v49
	v_cvt_pk_bf16_f32 v55, v50, v51
	global_store_dwordx4 v[220:221], v[60:63], off
	global_store_dwordx4 v[220:221], v[52:55], off offset:256
	v_lshl_add_u64 v[220:221], v[220:221], 0, s[98:99]
	v_mul_f32_e32 v32, v176, v32
	v_mul_f32_e32 v33, v176, v33
	v_mul_f32_e32 v34, v176, v34
	v_mul_f32_e32 v35, v176, v35
	v_mul_f32_e32 v36, v176, v36
	v_mul_f32_e32 v37, v176, v37
	v_mul_f32_e32 v38, v176, v38
	v_mul_f32_e32 v39, v176, v39
	v_mul_f32_e32 v40, v176, v40
	v_mul_f32_e32 v41, v176, v41
	v_mul_f32_e32 v42, v176, v42
	v_mul_f32_e32 v43, v176, v43
	v_mul_f32_e32 v44, v176, v44
	v_mul_f32_e32 v45, v176, v45
	v_mul_f32_e32 v46, v176, v46
	v_mul_f32_e32 v47, v176, v47
	v_max_f32_e32 v32, 0, v32
	v_max_f32_e32 v33, 0, v33
	v_max_f32_e32 v34, 0, v34
	v_max_f32_e32 v35, 0, v35
	v_max_f32_e32 v36, 0, v36
	v_max_f32_e32 v37, 0, v37
	v_max_f32_e32 v38, 0, v38
	v_max_f32_e32 v39, 0, v39
	v_max_f32_e32 v40, 0, v40
	v_max_f32_e32 v41, 0, v41
	v_max_f32_e32 v42, 0, v42
	v_max_f32_e32 v43, 0, v43
	v_max_f32_e32 v44, 0, v44
	v_max_f32_e32 v45, 0, v45
	v_max_f32_e32 v46, 0, v46
	v_max_f32_e32 v47, 0, v47
	v_mul_f32_e32 v32, v32, v32
	v_mul_f32_e32 v33, v33, v33
	v_mul_f32_e32 v34, v34, v34
	v_mul_f32_e32 v35, v35, v35
	v_mul_f32_e32 v36, v36, v36
	v_mul_f32_e32 v37, v37, v37
	v_mul_f32_e32 v38, v38, v38
	v_mul_f32_e32 v39, v39, v39
	v_mul_f32_e32 v40, v40, v40
	v_mul_f32_e32 v41, v41, v41
	v_mul_f32_e32 v42, v42, v42
	v_mul_f32_e32 v43, v43, v43
	v_mul_f32_e32 v44, v44, v44
	v_mul_f32_e32 v45, v45, v45
	v_mul_f32_e32 v46, v46, v46
	v_mul_f32_e32 v47, v47, v47
	v_cvt_pk_bf16_f32 v44, v44, v45
	v_cvt_pk_bf16_f32 v45, v46, v47
	v_cvt_pk_bf16_f32 v46, v40, v41
	v_cvt_pk_bf16_f32 v47, v42, v43
	v_cvt_pk_bf16_f32 v36, v36, v37
	v_cvt_pk_bf16_f32 v37, v38, v39
	v_cvt_pk_bf16_f32 v38, v32, v33
	v_cvt_pk_bf16_f32 v39, v34, v35
	global_store_dwordx4 v[220:221], v[44:47], off
	global_store_dwordx4 v[220:221], v[36:39], off offset:256
	v_lshl_add_u64 v[220:221], v[220:221], 0, s[98:99]
	v_mul_f32_e32 v16, v180, v16
	v_mul_f32_e32 v17, v180, v17
	v_mul_f32_e32 v18, v180, v18
	v_mul_f32_e32 v19, v180, v19
	v_mul_f32_e32 v20, v180, v20
	v_mul_f32_e32 v21, v180, v21
	v_mul_f32_e32 v22, v180, v22
	v_mul_f32_e32 v23, v180, v23
	v_mul_f32_e32 v24, v180, v24
	v_mul_f32_e32 v25, v180, v25
	v_mul_f32_e32 v26, v180, v26
	v_mul_f32_e32 v27, v180, v27
	v_mul_f32_e32 v28, v180, v28
	v_mul_f32_e32 v29, v180, v29
	v_mul_f32_e32 v30, v180, v30
	v_mul_f32_e32 v31, v180, v31
	v_max_f32_e32 v16, 0, v16
	v_max_f32_e32 v17, 0, v17
	v_max_f32_e32 v18, 0, v18
	v_max_f32_e32 v19, 0, v19
	v_max_f32_e32 v20, 0, v20
	v_max_f32_e32 v21, 0, v21
	v_max_f32_e32 v22, 0, v22
	v_max_f32_e32 v23, 0, v23
	v_max_f32_e32 v24, 0, v24
	v_max_f32_e32 v25, 0, v25
	v_max_f32_e32 v26, 0, v26
	v_max_f32_e32 v27, 0, v27
	v_max_f32_e32 v28, 0, v28
	v_max_f32_e32 v29, 0, v29
	v_max_f32_e32 v30, 0, v30
	v_max_f32_e32 v31, 0, v31
	v_mul_f32_e32 v16, v16, v16
	v_mul_f32_e32 v17, v17, v17
	v_mul_f32_e32 v18, v18, v18
	v_mul_f32_e32 v19, v19, v19
	v_mul_f32_e32 v20, v20, v20
	v_mul_f32_e32 v21, v21, v21
	v_mul_f32_e32 v22, v22, v22
	v_mul_f32_e32 v23, v23, v23
	v_mul_f32_e32 v24, v24, v24
	v_mul_f32_e32 v25, v25, v25
	v_mul_f32_e32 v26, v26, v26
	v_mul_f32_e32 v27, v27, v27
	v_mul_f32_e32 v28, v28, v28
	v_mul_f32_e32 v29, v29, v29
	v_mul_f32_e32 v30, v30, v30
	v_mul_f32_e32 v31, v31, v31
	v_cvt_pk_bf16_f32 v28, v28, v29
	v_cvt_pk_bf16_f32 v29, v30, v31
	v_cvt_pk_bf16_f32 v30, v24, v25
	v_cvt_pk_bf16_f32 v31, v26, v27
	v_cvt_pk_bf16_f32 v20, v20, v21
	v_cvt_pk_bf16_f32 v21, v22, v23
	v_cvt_pk_bf16_f32 v22, v16, v17
	v_cvt_pk_bf16_f32 v23, v18, v19
	global_store_dwordx4 v[220:221], v[28:31], off
	global_store_dwordx4 v[220:221], v[20:23], off offset:256
	v_lshl_add_u64 v[220:221], v[220:221], 0, s[98:99]
	v_mul_f32_e32 v0, v184, v0
	v_mul_f32_e32 v1, v184, v1
	v_mul_f32_e32 v2, v184, v2
	v_mul_f32_e32 v3, v184, v3
	v_mul_f32_e32 v4, v184, v4
	v_mul_f32_e32 v5, v184, v5
	v_mul_f32_e32 v6, v184, v6
	v_mul_f32_e32 v7, v184, v7
	v_mul_f32_e32 v8, v184, v8
	v_mul_f32_e32 v9, v184, v9
	v_mul_f32_e32 v10, v184, v10
	v_mul_f32_e32 v11, v184, v11
	v_mul_f32_e32 v12, v184, v12
	v_mul_f32_e32 v13, v184, v13
	v_mul_f32_e32 v14, v184, v14
	v_mul_f32_e32 v15, v184, v15
	v_max_f32_e32 v0, 0, v0
	v_max_f32_e32 v1, 0, v1
	v_max_f32_e32 v2, 0, v2
	v_max_f32_e32 v3, 0, v3
	v_max_f32_e32 v4, 0, v4
	v_max_f32_e32 v5, 0, v5
	v_max_f32_e32 v6, 0, v6
	v_max_f32_e32 v7, 0, v7
	v_max_f32_e32 v8, 0, v8
	v_max_f32_e32 v9, 0, v9
	v_max_f32_e32 v10, 0, v10
	v_max_f32_e32 v11, 0, v11
	v_max_f32_e32 v12, 0, v12
	v_max_f32_e32 v13, 0, v13
	v_max_f32_e32 v14, 0, v14
	v_max_f32_e32 v15, 0, v15
	v_mul_f32_e32 v0, v0, v0
	v_mul_f32_e32 v1, v1, v1
	v_mul_f32_e32 v2, v2, v2
	v_mul_f32_e32 v3, v3, v3
	v_mul_f32_e32 v4, v4, v4
	v_mul_f32_e32 v5, v5, v5
	v_mul_f32_e32 v6, v6, v6
	v_mul_f32_e32 v7, v7, v7
	v_mul_f32_e32 v8, v8, v8
	v_mul_f32_e32 v9, v9, v9
	v_mul_f32_e32 v10, v10, v10
	v_mul_f32_e32 v11, v11, v11
	v_mul_f32_e32 v12, v12, v12
	v_mul_f32_e32 v13, v13, v13
	v_mul_f32_e32 v14, v14, v14
	v_mul_f32_e32 v15, v15, v15
	v_cvt_pk_bf16_f32 v12, v12, v13
	v_cvt_pk_bf16_f32 v13, v14, v15
	v_cvt_pk_bf16_f32 v14, v8, v9
	v_cvt_pk_bf16_f32 v15, v10, v11
	v_cvt_pk_bf16_f32 v4, v4, v5
	v_cvt_pk_bf16_f32 v5, v6, v7
	v_cvt_pk_bf16_f32 v6, v0, v1
	v_cvt_pk_bf16_f32 v7, v2, v3
	global_store_dwordx4 v[220:221], v[12:15], off
	global_store_dwordx4 v[220:221], v[4:7], off offset:256
	s_andn2_b64 vcc, exec, s[4:5]
	s_mov_b64 s[4:5], -1
	s_cbranch_vccnz .LBB0_1536
	s_andn2_b64 vcc, exec, s[6:7]
	s_cbranch_vccnz .LBB0_1535
	s_barrier
	s_branch .LBB0_1535
